# panel-group seams fall back to the global barrier for the whole grid (uniform flag) if any panel group straddles XCDs, instead of per-workgroup write-backs
# speedup vs baseline: 1.0014x; 1.0014x over previous
.Lin_seam2:
	s_waitcnt vmcnt(0)
	s_barrier
	s_mov_b64 s[0:1], exec
	v_readlane_b32 s2, v252, 9
	v_readlane_b32 s3, v252, 10
	s_and_b64 s[2:3], s[0:1], s[2:3]
	s_mov_b64 exec, s[2:3]
	s_cbranch_execz .LBB0_359
	v_readlane_b32 s30, v252, 11
	v_readlane_b32 s31, v252, 12
	v_readlane_b32 s32, v252, 13
	v_mov_b32_e32 v5, 1
	v_mov_b32_e32 v22, 0
	s_add_u32 s34, s30, 0x1400
	s_addc_u32 s35, s31, 0
	s_lshl_b32 s32, s32, 8
	s_add_u32 s40, s30, 0x3400
	s_addc_u32 s41, s31, 0
	v_mov_b32_e32 v4, s32
	s_mov_b32 s42, 0
	s_and_b32 s36, s54, 63
	s_lshl_b32 s36, s36, 2
	s_addk_i32 s36, 0x3800
	v_mov_b32_e32 v9, s36
	global_load_dword v10, v9, s[30:31] sc1
	global_load_dword v11, v9, s[30:31] offset:256 sc1
	global_load_dword v12, v9, s[30:31] offset:512 sc1
	global_load_dword v13, v9, s[30:31] offset:768 sc1
	global_atomic_add v6, v4, v5, s[34:35] sc0
	buffer_inv sc1
	s_mul_i32 s33, s86, 2
	s_mul_i32 s39, s98, 2
	s_waitcnt vmcnt(0)
	v_readfirstlane_b32 s38, v6
	v_readfirstlane_b32 s36, v10
	v_readfirstlane_b32 s37, v11
	v_readfirstlane_b32 s43, v12
	v_readfirstlane_b32 s44, v13
	s_cmp_lg_u32 s36, s37
	s_cselect_b32 s99, 1, 0
	s_cmp_lg_u32 s36, s43
	s_cselect_b32 s37, 1, 0
	s_or_b32 s99, s99, s37
	s_cmp_lg_u32 s36, s44
	s_cselect_b32 s37, 1, 0
	s_or_b32 s99, s99, s37
	s_cmp_eq_u32 s36, 0
	s_cselect_b32 s37, 1, 0
	s_or_b32 s99, s99, s37
	s_cmp_eq_u32 s99, 0
	s_cbranch_scc1 .Lxb2_homog
	v_mov_b32_e32 v9, 0x3c00
	global_atomic_add v9, v5, s[30:31]
.Lxb2_homog:
	v_mov_b32_e32 v7, s98
	s_add_i32 s38, s38, 1
	s_cmp_lg_u32 s38, s39
	s_cbranch_scc1 .Lxb2_spin
	buffer_wbl2 sc1
	s_waitcnt vmcnt(0)
	global_atomic_add v22, v7, s[40:41]

.LBB0_610:
	s_waitcnt vmcnt(0)
	s_barrier
	s_mov_b64 s[0:1], exec
	v_readlane_b32 s2, v252, 9
	v_readlane_b32 s3, v252, 10
	s_and_b64 s[2:3], s[0:1], s[2:3]
	s_mov_b64 exec, s[2:3]
	s_cbranch_execz .LBB0_662
	v_readlane_b32 s30, v252, 11
	v_readlane_b32 s31, v252, 12
	v_readlane_b32 s32, v252, 13
	v_mov_b32_e32 v5, 1
	v_mov_b32_e32 v22, 0
	s_add_u32 s34, s30, 0x1400
	s_addc_u32 s35, s31, 0
	s_lshl_b32 s32, s32, 8
	s_add_u32 s40, s30, 0x3400
	s_addc_u32 s41, s31, 0
	v_mov_b32_e32 v4, s32
	s_mov_b32 s42, 0
	v_mov_b32_e32 v9, 0x3c00
	global_load_dword v10, v9, s[30:31] sc1
	global_atomic_add v6, v4, v5, s[34:35] sc0
	buffer_inv sc1
	s_mul_i32 s33, s86, 3
	s_mul_i32 s39, s98, 3
	s_waitcnt vmcnt(0)
	v_readfirstlane_b32 s38, v6
	v_readfirstlane_b32 s36, v10
	s_cmp_lg_u32 s36, 0
	s_cselect_b32 s99, 1, 0
	v_mov_b32_e32 v7, s98
	s_add_i32 s38, s38, 1
	s_cmp_lg_u32 s38, s39
	s_cbranch_scc1 .Lxb3_spin
	buffer_wbl2 sc1
	s_waitcnt vmcnt(0)
	global_atomic_add v22, v7, s[40:41]

.LBB0_724:
	s_waitcnt vmcnt(0)
	s_barrier
	s_mov_b64 s[0:1], exec
	v_readlane_b32 s2, v252, 9
	v_readlane_b32 s3, v252, 10
	s_and_b64 s[2:3], s[0:1], s[2:3]
	s_mov_b64 exec, s[2:3]
	s_cbranch_execz .LBB0_776
	v_readlane_b32 s30, v252, 11
	v_readlane_b32 s31, v252, 12
	v_readlane_b32 s32, v252, 48
	v_mov_b32_e32 v5, 1
	v_mov_b32_e32 v22, 0
	s_add_u32 s36, s30, 0x10000
	s_addc_u32 s37, s31, 0
	s_and_b32 s32, s32, 63
	s_lshl_b32 s32, s32, 8
	s_add_u32 s34, s30, 0x4000
	s_addc_u32 s35, s31, 0
	v_mov_b32_e32 v4, s32
	global_atomic_add v22, v5, s[36:37]
	s_cmpk_lg_u32 s86, 0x100
	s_cbranch_scc1 .Lxb4_global
	s_cmp_lg_u32 s99, 0
	s_cbranch_scc1 .Lxb4_global
	global_atomic_add v4, v5, s[34:35]
	buffer_inv sc1
	s_mov_b32 s42, 0

.LBB0_1008:
	s_waitcnt vmcnt(0)
	s_barrier
	s_mov_b64 s[0:1], exec
	v_readlane_b32 s2, v252, 9
	v_readlane_b32 s3, v252, 10
	s_and_b64 s[2:3], s[0:1], s[2:3]
	s_mov_b64 exec, s[2:3]
	s_cbranch_execz .LBB0_1060
	v_readlane_b32 s30, v252, 11
	v_readlane_b32 s31, v252, 12
	v_readlane_b32 s32, v252, 48
	v_mov_b32_e32 v5, 1
	v_mov_b32_e32 v22, 0
	s_add_u32 s36, s30, 0x10800
	s_addc_u32 s37, s31, 0
	s_and_b32 s32, s32, 63
	s_lshl_b32 s32, s32, 8
	s_add_u32 s34, s30, 0x8000
	s_addc_u32 s35, s31, 0
	v_mov_b32_e32 v4, s32
	global_atomic_add v22, v5, s[36:37]
	s_cmpk_lg_u32 s86, 0x100
	s_cbranch_scc1 .Lxb5_global
	s_cmp_lg_u32 s99, 0
	s_cbranch_scc1 .Lxb5_global
	global_atomic_add v4, v5, s[34:35]
	buffer_inv sc1
	s_mov_b32 s42, 0

.LBB0_1091:
	s_waitcnt vmcnt(0)
	s_barrier
	s_mov_b64 s[0:1], exec
	v_readlane_b32 s6, v252, 9
	v_readlane_b32 s7, v252, 10
	s_and_b64 s[6:7], s[0:1], s[6:7]
	s_mov_b64 exec, s[6:7]
	s_cbranch_execz .LBB0_1143
	v_readlane_b32 s30, v252, 11
	v_readlane_b32 s31, v252, 12
	v_readlane_b32 s32, v252, 48
	v_mov_b32_e32 v5, 1
	v_mov_b32_e32 v22, 0
	s_add_u32 s36, s30, 0x11000
	s_addc_u32 s37, s31, 0
	s_and_b32 s32, s32, 63
	s_lshl_b32 s32, s32, 8
	s_add_u32 s34, s30, 0xc000
	s_addc_u32 s35, s31, 0
	v_mov_b32_e32 v4, s32
	global_atomic_add v22, v5, s[36:37]
	s_cmpk_lg_u32 s86, 0x100
	s_cbranch_scc1 .Lxb6_global
	s_cmp_lg_u32 s99, 0
	s_cbranch_scc1 .Lxb6_global
	global_atomic_add v4, v5, s[34:35]
	buffer_inv sc1
	s_mov_b32 s42, 0
